# P0 rows loop: row-0 loads drained before row-1 loads are issued (fewer concurrent DRAM streams) - repeat
# speedup vs baseline: 1.0168x; 1.0065x over previous
.LBB0_38:
	s_add_i32 s28, s56, s58
	s_cmpk_lt_i32 s28, 0x4000
	s_cselect_b32 s16, s28, s56
	s_ashr_i32 s57, s56, 31
	s_lshl_b64 s[46:47], s[56:57], 12
	v_lshl_add_u64 v[34:35], v[2:3], 0, s[46:47]
	global_load_dwordx4 v[18:21], v[4:5], off
	s_ashr_i32 s17, s16, 31
	global_load_dwordx4 v[22:25], v[34:35], off
	global_load_dwordx4 v[26:29], v[34:35], off offset:1024
	global_load_dwordx4 v[30:33], v[34:35], off offset:3072
	s_nop 0
	global_load_dwordx4 v[34:37], v[34:35], off offset:2048
	s_lshl_b64 s[0:1], s[56:57], 10
	s_lshl_b64 s[50:51], s[16:17], 12
	s_lshl_b64 s[46:47], s[16:17], 10
	v_lshl_add_u64 v[38:39], v[6:7], 0, s[0:1]
	v_lshl_add_u64 v[64:65], v[2:3], 0, s[50:51]
	global_load_dwordx4 v[38:41], v[38:39], off nt
	s_waitcnt vmcnt(0)
	v_lshl_add_u64 v[66:67], v[6:7], 0, s[46:47]
	global_load_dwordx4 v[42:45], v[64:65], off
	global_load_dwordx4 v[46:49], v[64:65], off offset:1024
	global_load_dwordx4 v[50:53], v[64:65], off offset:3072
	global_load_dwordx4 v[54:57], v[64:65], off offset:2048
	global_load_dwordx4 v[58:61], v[66:67], off nt
	s_lshl_b64 s[0:1], s[16:17], 11
	v_lshl_add_u64 v[68:69], v[8:9], 0, s[0:1]
	s_lshl_b64 s[48:49], s[56:57], 11
	v_lshl_add_u64 v[62:63], v[8:9], 0, s[48:49]
	s_waitcnt vmcnt(9)
	v_pk_mul_f32 v[64:65], v[24:25], v[24:25]
	v_pk_mul_f32 v[66:67], v[22:23], v[22:23]
	s_waitcnt vmcnt(8)
	v_pk_mul_f32 v[70:71], v[28:29], v[28:29]
	v_pk_mul_f32 v[72:73], v[26:27], v[26:27]
	s_waitcnt vmcnt(6)
	v_mul_f32_e32 v74, v35, v35
	v_mul_f32_e32 v76, v37, v37
	v_pk_mov_b32 v[78:79], v[66:67], v[64:65] op_sel:[1,0]
	v_mov_b32_e32 v67, v65
	s_waitcnt vmcnt(4)
	v_pk_mul_f32 v[64:65], v[44:45], v[44:45]
	v_pk_mul_f32 v[80:81], v[42:43], v[42:43]
	v_pk_mov_b32 v[82:83], v[72:73], v[70:71] op_sel:[1,0]
	v_mov_b32_e32 v73, v71
	s_waitcnt vmcnt(3)
	v_pk_mul_f32 v[70:71], v[48:49], v[48:49]
	v_pk_mul_f32 v[84:85], v[46:47], v[46:47]
	v_mul_f32_e32 v89, v32, v32
	v_mul_f32_e32 v90, v33, v33
	v_pk_fma_f32 v[74:75], v[34:35], v[34:35], v[74:75] op_sel_hi:[1,1,0]
	v_pk_fma_f32 v[76:77], v[36:37], v[36:37], v[76:77] op_sel_hi:[1,1,0]
	v_pk_add_f32 v[66:67], v[78:79], v[66:67]
	v_pk_mov_b32 v[78:79], v[80:81], v[64:65] op_sel:[1,0]
	v_mov_b32_e32 v81, v65
	v_pk_add_f32 v[64:65], v[82:83], v[72:73]
	v_pk_mov_b32 v[72:73], v[84:85], v[70:71] op_sel:[1,0]
	v_mov_b32_e32 v85, v71
	v_mul_f32_e32 v87, v31, v31
	s_waitcnt vmcnt(1)
	v_mul_f32_e32 v86, v55, v55
	v_mul_f32_e32 v88, v57, v57
	v_mov_b32_e32 v75, v89
	v_mov_b32_e32 v77, v90
	v_pk_add_f32 v[78:79], v[78:79], v[80:81]
	v_pk_add_f32 v[72:73], v[72:73], v[84:85]
	v_mul_f32_e32 v17, v30, v30
	v_mul_f32_e32 v91, v50, v50
	v_mul_f32_e32 v92, v51, v51
	v_mul_f32_e32 v93, v52, v52
	v_mul_f32_e32 v94, v53, v53
	v_pk_fma_f32 v[70:71], v[54:55], v[54:55], v[86:87] op_sel_hi:[1,1,0]
	v_pk_fma_f32 v[82:83], v[56:57], v[56:57], v[88:89] op_sel_hi:[1,1,0]
	v_pk_add_f32 v[66:67], v[66:67], v[66:67] op_sel:[0,1] op_sel_hi:[1,0]
	v_pk_add_f32 v[64:65], v[64:65], v[64:65] op_sel:[0,1] op_sel_hi:[1,0]
	v_pk_add_f32 v[74:75], v[74:75], v[76:77]
	v_pk_add_f32 v[76:77], v[78:79], v[78:79] op_sel:[0,1] op_sel_hi:[1,0]
	v_pk_add_f32 v[72:73], v[72:73], v[72:73] op_sel:[0,1] op_sel_hi:[1,0]
	v_mov_b32_e32 v71, v93
	v_mov_b32_e32 v83, v94
	v_mov_b32_e32 v67, v17
	v_mov_b32_e32 v65, v87
	v_mov_b32_e32 v77, v91
	v_mov_b32_e32 v73, v92
	v_pk_add_f32 v[70:71], v[70:71], v[82:83]
	v_pk_add_f32 v[64:65], v[66:67], v[64:65]
	v_pk_add_f32 v[66:67], v[76:77], v[72:73]
	v_pk_add_f32 v[64:65], v[64:65], v[74:75]
	v_pk_add_f32 v[66:67], v[66:67], v[70:71]
	v_mov_b32_e32 v71, v64
	v_mov_b32_e32 v70, v66
	v_mov_b32_e32 v64, v67
	v_pk_add_f32 v[64:65], v[70:71], v[64:65]
	ds_bpermute_b32 v67, v11, v65
	ds_bpermute_b32 v66, v11, v64
	s_waitcnt lgkmcnt(0)
	v_pk_add_f32 v[64:65], v[64:65], v[66:67]
	ds_bpermute_b32 v67, v12, v65
	ds_bpermute_b32 v66, v12, v64
	s_waitcnt lgkmcnt(0)
	v_pk_add_f32 v[64:65], v[64:65], v[66:67]
	ds_bpermute_b32 v67, v13, v65
	ds_bpermute_b32 v66, v13, v64
	s_waitcnt lgkmcnt(0)
	v_pk_add_f32 v[64:65], v[64:65], v[66:67]
	ds_bpermute_b32 v67, v14, v65
	ds_bpermute_b32 v66, v14, v64
	s_waitcnt lgkmcnt(0)
	v_pk_add_f32 v[64:65], v[64:65], v[66:67]
	ds_bpermute_b32 v67, v15, v65
	ds_bpermute_b32 v66, v15, v64
	s_waitcnt lgkmcnt(0)
	v_pk_add_f32 v[64:65], v[64:65], v[66:67]
	ds_bpermute_b32 v67, v16, v65
	ds_bpermute_b32 v66, v16, v64
	s_waitcnt lgkmcnt(0)
	v_pk_add_f32 v[64:65], v[64:65], v[66:67]
	s_nop 0
	v_pk_fma_f32 v[64:65], v[64:65], s[14:15], v[10:11] op_sel_hi:[1,0,0]
	s_nop 0
	v_mul_f32_e32 v17, 0x4b800000, v65
	v_cmp_gt_f32_e64 s[0:1], s15, v65
	v_mul_f32_e32 v66, 0x4b800000, v64
	v_cmp_gt_f32_e32 vcc, s15, v64
	v_cndmask_b32_e64 v17, v65, v17, s[0:1]
	v_rsq_f32_e32 v17, v17
	v_cndmask_b32_e32 v64, v64, v66, vcc
	v_rsq_f32_e32 v65, v64
	v_mul_f32_e32 v64, 0x45800000, v17
	v_cndmask_b32_e64 v64, v17, v64, s[0:1]
	v_mul_f32_e32 v66, 0x45800000, v65
	v_cndmask_b32_e32 v66, v65, v66, vcc
	v_pk_mul_f32 v[22:23], v[64:65], v[22:23] op_sel_hi:[0,1]
	v_pk_mul_f32 v[24:25], v[64:65], v[24:25] op_sel_hi:[0,1]
	v_pk_mul_f32 v[42:43], v[66:67], v[42:43] op_sel_hi:[0,1]
	v_pk_mul_f32 v[44:45], v[66:67], v[44:45] op_sel_hi:[0,1]
	v_pk_mul_f32 v[24:25], v[24:25], v[20:21]
	v_pk_mul_f32 v[22:23], v[22:23], v[18:19]
	v_pk_mul_f32 v[20:21], v[44:45], v[20:21]
	v_pk_mul_f32 v[18:19], v[42:43], v[18:19]
	v_cvt_pk_bf16_f32 v22, v22, v23
	v_cvt_pk_bf16_f32 v23, v24, v25
	v_cvt_pk_bf16_f32 v18, v18, v19
	v_cvt_pk_bf16_f32 v19, v20, v21
	global_store_dwordx2 v[62:63], v[22:23], off
	global_store_dwordx2 v[68:69], v[18:19], off
	global_load_dwordx4 v[18:21], v[4:5], off offset:1024
	v_pk_mul_f32 v[22:23], v[64:65], v[26:27] op_sel_hi:[0,1]
	v_pk_mul_f32 v[24:25], v[64:65], v[28:29] op_sel_hi:[0,1]
	v_pk_mul_f32 v[26:27], v[66:67], v[46:47] op_sel_hi:[0,1]
	v_pk_mul_f32 v[28:29], v[66:67], v[48:49] op_sel_hi:[0,1]
	s_lshl_b64 s[0:1], s[56:57], 9
	v_pk_mul_f32 v[30:31], v[64:65], v[30:31] op_sel_hi:[0,1]
	v_pk_mul_f32 v[32:33], v[64:65], v[32:33] op_sel_hi:[0,1]
	s_add_i32 s56, s28, s58
	s_waitcnt vmcnt(0)
	v_pk_mul_f32 v[24:25], v[24:25], v[20:21]
	v_pk_mul_f32 v[22:23], v[22:23], v[18:19]
	v_pk_mul_f32 v[20:21], v[28:29], v[20:21]
	v_pk_mul_f32 v[18:19], v[26:27], v[18:19]
	v_cvt_pk_bf16_f32 v22, v22, v23
	v_cvt_pk_bf16_f32 v23, v24, v25
	v_cvt_pk_bf16_f32 v18, v18, v19
	v_cvt_pk_bf16_f32 v19, v20, v21
	global_store_dwordx2 v[62:63], v[22:23], off offset:512
	global_store_dwordx2 v[68:69], v[18:19], off offset:512
	global_load_dwordx4 v[18:21], v[4:5], off offset:2048
	v_pk_mul_f32 v[22:23], v[64:65], v[34:35] op_sel_hi:[0,1]
	v_pk_mul_f32 v[24:25], v[64:65], v[36:37] op_sel_hi:[0,1]
	v_pk_mul_f32 v[26:27], v[66:67], v[54:55] op_sel_hi:[0,1]
	v_pk_mul_f32 v[28:29], v[66:67], v[56:57] op_sel_hi:[0,1]
	v_pk_mul_f32 v[34:35], v[66:67], v[50:51] op_sel_hi:[0,1]
	v_pk_mul_f32 v[36:37], v[66:67], v[52:53] op_sel_hi:[0,1]
	s_waitcnt vmcnt(0)
	v_pk_mul_f32 v[24:25], v[24:25], v[20:21]
	v_pk_mul_f32 v[22:23], v[22:23], v[18:19]
	v_pk_mul_f32 v[20:21], v[28:29], v[20:21]
	v_pk_mul_f32 v[18:19], v[26:27], v[18:19]
	v_cvt_pk_bf16_f32 v22, v22, v23
	v_cvt_pk_bf16_f32 v23, v24, v25
	v_cvt_pk_bf16_f32 v18, v18, v19
	v_cvt_pk_bf16_f32 v19, v20, v21
	global_store_dwordx2 v[62:63], v[22:23], off offset:1024
	global_store_dwordx2 v[68:69], v[18:19], off offset:1024
	global_load_dwordx4 v[18:21], v[4:5], off offset:3072
	v_lshl_add_u64 v[22:23], v[0:1], 0, s[0:1]
	s_lshl_b64 s[0:1], s[16:17], 9
	s_cmpk_gt_i32 s56, 0x3fff
	v_lshl_add_u64 v[24:25], v[0:1], 0, s[0:1]
	v_cvt_pk_bf16_f32 v26, v38, v39
	v_cvt_pk_bf16_f32 v27, v40, v41
	v_cvt_pk_bf16_f32 v28, v58, v59
	v_cvt_pk_bf16_f32 v29, v60, v61
	s_waitcnt vmcnt(0)
	v_pk_mul_f32 v[32:33], v[32:33], v[20:21]
	v_pk_mul_f32 v[30:31], v[30:31], v[18:19]
	v_pk_mul_f32 v[20:21], v[36:37], v[20:21]
	v_pk_mul_f32 v[18:19], v[34:35], v[18:19]
	v_cvt_pk_bf16_f32 v30, v30, v31
	v_cvt_pk_bf16_f32 v31, v32, v33
	v_cvt_pk_bf16_f32 v18, v18, v19
	v_cvt_pk_bf16_f32 v19, v20, v21
	global_store_dwordx2 v[62:63], v[30:31], off offset:1536
	global_store_dwordx2 v[68:69], v[18:19], off offset:1536
	global_store_dwordx2 v[22:23], v[26:27], off
	global_store_dwordx2 v[24:25], v[28:29], off
	s_cbranch_scc0 .LBB0_38
